# per-phase static priorities: waves 4-7 prio 1 in all phases except E2 mixers where waves 0-3 (GLA) get prio 1
# speedup vs baseline: 1.0028x; 1.0028x over previous
; #define LAS __attribute__((address_space(3)))
; __device__ __forceinline__ int half_id() { return __builtin_amdgcn_readfirstlane((int)(threadIdx.x >> 8)); }
; __global__ void __launch_bounds__(512, 2) fwd_megakernel(Params p) {
;   cg::grid_group grid = cg::this_grid();
;   if (p.inv_freq[0] < 0.f) grid.sync();
;   volatile LAS unsigned* xst = (volatile LAS unsigned*)(smem_all + 2 * SMEM_BYTES);
;   if (threadIdx.x == 0) { xst[0] = 0u; xst[1] = 0u; xst[2] = 0u; xst[3] = 0u; }
;   __syncthreads();
_Z14fwd_megakernel6Params:
	v_readfirstlane_b32 s100, v0
	s_nop 3
	s_and_b32 s100, s100, 0x3ff
	s_lshr_b32 s100, s100, 8
	s_load_dword s3, s[0:1], 0xd0
	s_add_u32 s28, s0, 0x110
	s_addc_u32 s29, s1, 0
	s_waitcnt lgkmcnt(0)
	v_cmp_lt_f32_e64 s[4:5], s3, 0
	s_and_b64 vcc, exec, s[4:5]
	s_cbranch_vccnz .LBB0_2
	v_and_b32_e32 v175, 0x3ff, v0
	s_load_dword s33, s[0:1], 0x118
	s_cbranch_execz .LBB0_3
	s_branch .LBB0_14

; #define LAS __attribute__((address_space(3)))
; __device__ __forceinline__ unsigned xb_ld(unsigned* p)              { return __hip_atomic_load(p, __ATOMIC_RELAXED, __HIP_MEMORY_SCOPE_AGENT); }
; __device__ __forceinline__ unsigned xb_add(unsigned* p, unsigned v) { return __hip_atomic_fetch_add(p, v, __ATOMIC_RELAXED, __HIP_MEMORY_SCOPE_AGENT); }
; __device__ __forceinline__ unsigned xb_xcc_id() { return (unsigned)__builtin_amdgcn_s_getreg((3 << 11) | 20) & 0xFu; }
; __device__ __forceinline__ XcdBarrier xcd_barrier_post(unsigned* bar, volatile LAS unsigned* st) {
;     XcdBarrier b; b.bar = bar; b.x = xb_xcc_id(); b.st = st;
;     if (threadIdx.x == 0) (void)xb_add(&bar[XB_XCNT(b.x)], 1u);
;     return b;
; }
; __device__ __forceinline__ void xcd_barrier_complete(unsigned* bar, unsigned x, unsigned& nloc, unsigned& nx) {
;     const unsigned G = gridDim.x * gridDim.y * gridDim.z;
;     unsigned sum, cnt, mine, sp = 0u;
;     for (;;) {
;         sum = 0u; cnt = 0u; mine = 0u;
; #pragma unroll
;         for (unsigned j = 0; j < 16; ++j) { const unsigned c = xb_ld(&bar[XB_XCNT(j)]); sum += c; cnt += (c > 0u) ? 1u : 0u; mine = (j == x) ? c : mine; }
;         if (sum == G) break;
;         __builtin_amdgcn_s_sleep(1);
;         if ((++sp & 255u) == 0u) { if (xb_ld(&bar[XB_TMO])) break; if (sp > XB_SPIN_CAP) { atomicAdd(&bar[XB_TMO], 1u); break; } }
;     }
;     nloc = mine > 0u ? mine : 1u; nx = cnt > 0u ? cnt : 1u;
; }
; __global__ void __launch_bounds__(512, 2) fwd_megakernel(Params p) {
;     ...
;   xcd_barrier(xb);
; #pragma unroll 1
;   for (int layer = 0; layer < 4; ++layer) {
;     const int j = layer >> 1;
;     if ((layer & 1) == 0) {
.LBB0_570:
	s_or_b64 exec, exec, s[2:3]
	s_barrier
	s_cmp_lg_u32 s100, 0
	s_cbranch_scc1 .Lp0_h1
	s_setprio 0
	s_branch .Lp0_d
.Lp0_h1:
	s_setprio 1
.Lp0_d:
	s_load_dwordx2 s[10:11], s[0:1], 0x110
	v_lshl_add_u64 v[0:1], v[0:1], 2, s[38:39]
	s_mov_b32 s93, 0
	s_mov_b32 s94, s93
	s_mov_b32 s95, s93
	s_waitcnt lgkmcnt(0)
	s_lshr_b32 s75, s10, 3
	s_add_u32 s80, s68, 0xf800200
	s_addc_u32 s81, s69, 0
	s_add_u32 s6, s68, 0xf800400
	s_mul_i32 s2, s11, s10
	s_addc_u32 s7, s69, 0
	s_mul_i32 s76, s2, s33
	s_add_u32 s2, s68, 0xf800500
	s_addc_u32 s3, s69, 0
	v_writelane_b32 v241, s2, 4
	s_mov_b32 s92, s93
	v_mov_b64_e32 v[238:239], s[94:95]
	v_writelane_b32 v241, s3, 5
	s_add_u32 s2, s68, 0xf800600
	s_addc_u32 s3, s69, 0
	v_writelane_b32 v241, s2, 6
	v_mov_b64_e32 v[236:237], s[92:93]
	s_mov_b64 s[94:95], s[6:7]
	v_writelane_b32 v241, s3, 7
	s_add_u32 s2, s68, 0xf800700
	s_addc_u32 s3, s69, 0
	v_writelane_b32 v241, s2, 8
	s_mov_b32 s88, 0.5
	s_movk_i32 s86, 0xff80
	v_writelane_b32 v241, s3, 9
	s_add_u32 s2, s68, 0xf800800
	s_addc_u32 s3, s69, 0
	v_writelane_b32 v241, s2, 10
	v_and_b32_e32 v186, 0xff, v175
	v_mov_b32_e32 v12, 0
	v_writelane_b32 v241, s3, 11
	s_add_u32 s2, s68, 0xf800900
	s_addc_u32 s3, s69, 0
	v_writelane_b32 v241, s2, 12
	v_mov_b32_e32 v187, 0x358637bd
	v_mov_b32_e32 v188, 0x25000
	v_writelane_b32 v241, s3, 13
	s_add_u32 s2, s68, 0xf800a00
	s_addc_u32 s3, s69, 0
	v_writelane_b32 v241, s2, 14
	v_mov_b32_e32 v189, 0x25004
	v_mov_b32_e32 v190, 1
	v_writelane_b32 v241, s3, 15
	s_add_u32 s2, s68, 0xf800b00
	s_addc_u32 s3, s69, 0
	v_writelane_b32 v241, s2, 16
	v_mov_b32_e32 v192, 0x3ecc95a3
	s_mov_b32 s89, 0x3eaaaaab
	v_writelane_b32 v241, s3, 17
	s_add_u32 s2, s68, 0xf800c00
	s_addc_u32 s3, s69, 0
	v_writelane_b32 v241, s2, 18
	v_not_b32_e32 v193, 63
	v_mov_b32_e32 v194, 0xff800000
	v_writelane_b32 v241, s3, 19
	s_add_u32 s2, s68, 0xf800d00
	s_addc_u32 s3, s69, 0
	v_writelane_b32 v241, s2, 20
	v_mov_b32_e32 v195, 0x1680000
	v_mov_b32_e32 v196, 0x12800
	v_writelane_b32 v241, s3, 21
	s_add_u32 s2, s68, 0xf800e00
	s_addc_u32 s3, s69, 0
	v_writelane_b32 v241, s2, 22
	v_mov_b32_e32 v197, 0x41b17218
	v_mov_b32_e32 v198, 0x48
	v_writelane_b32 v241, s3, 23
	s_add_u32 s2, s68, 0xf800f00
	s_addc_u32 s3, s69, 0
	v_writelane_b32 v241, s2, 24
	v_mov_b32_e32 v199, 0x7f800000
	v_mov_b32_e32 v200, 0x7fc00000
	v_writelane_b32 v241, s3, 25
	s_add_u32 s2, s68, 0xf801000
	s_addc_u32 s3, s69, 0
	v_writelane_b32 v241, s2, 26
	s_mov_b32 s82, 0x10000
	s_mov_b32 s33, 0x800000
	v_writelane_b32 v241, s3, 27
	s_add_u32 s2, s68, 0xf801100
	s_addc_u32 s3, s69, 0
	v_writelane_b32 v241, s2, 28
	s_movk_i32 s83, 0xc00
	s_movk_i32 s14, 0x1000
	v_writelane_b32 v241, s3, 29
	s_add_u32 s2, s68, 0xf801200
	s_addc_u32 s3, s69, 0
	s_add_u32 s78, s68, 0xf801300
	s_addc_u32 s79, s69, 0
	v_writelane_b32 v241, s2, 30
	s_cmp_eq_u32 s64, 15
	s_cselect_b64 s[4:5], -1, 0
	v_writelane_b32 v241, s3, 31
	v_writelane_b32 v241, s4, 32
	s_cmp_eq_u32 s64, 14
	s_mov_b32 s2, 0x20000
	v_writelane_b32 v241, s5, 33
	s_cselect_b64 s[4:5], -1, 0
	v_writelane_b32 v241, s4, 34
	s_cmp_eq_u32 s64, 13
	s_movk_i32 s15, 0x810
	v_writelane_b32 v241, s5, 35
	s_cselect_b64 s[4:5], -1, 0
	v_writelane_b32 v241, s4, 36
	s_cmp_eq_u32 s64, 12
	s_movk_i32 s16, 0x80f
	v_writelane_b32 v241, s5, 37
	s_cselect_b64 s[4:5], -1, 0
	v_writelane_b32 v241, s4, 38
	s_cmp_eq_u32 s64, 11
	s_mov_b32 s17, 0xff800000
	v_writelane_b32 v241, s5, 39
	s_cselect_b64 s[4:5], -1, 0
	v_writelane_b32 v241, s4, 40
	s_cmp_eq_u32 s64, 10
	s_mov_b32 s18, 0xbfb8aa3b
	v_writelane_b32 v241, s5, 41
	s_cselect_b64 s[4:5], -1, 0
	v_writelane_b32 v241, s4, 42
	s_cmp_eq_u32 s64, 9
	s_movk_i32 s19, 0x110
	v_writelane_b32 v241, s5, 43
	s_cselect_b64 s[4:5], -1, 0
	v_writelane_b32 v241, s4, 44
	s_cmp_eq_u32 s64, 8
	s_mov_b32 s20, 0x3f317217
	v_writelane_b32 v241, s5, 45
	s_cselect_b64 s[4:5], -1, 0
	v_writelane_b32 v241, s4, 46
	s_cmp_eq_u32 s64, 7
	s_mov_b32 s21, 0x7f800000
	v_writelane_b32 v241, s5, 47
	s_cselect_b64 s[4:5], -1, 0
	v_writelane_b32 v241, s4, 48
	s_cmp_eq_u32 s64, 6
	s_mov_b32 s22, 0xfffffe0
	v_writelane_b32 v241, s5, 49
	s_cselect_b64 s[4:5], -1, 0
	v_writelane_b32 v241, s4, 50
	s_cmp_eq_u32 s64, 5
	s_movk_i32 s23, 0x80e
	v_writelane_b32 v241, s5, 51
	s_cselect_b64 s[4:5], -1, 0
	v_writelane_b32 v241, s4, 52
	s_cmp_eq_u32 s64, 4
	s_movk_i32 s24, 0x80d
	v_writelane_b32 v241, s5, 53
	s_cselect_b64 s[4:5], -1, 0
	v_writelane_b32 v241, s4, 54
	s_cmp_eq_u32 s64, 3
	s_movk_i32 s25, 0x80c
	v_writelane_b32 v241, s5, 55
	s_cselect_b64 s[4:5], -1, 0
	v_writelane_b32 v241, s4, 56
	s_cmp_eq_u32 s64, 2
	s_movk_i32 s26, 0x80b
	v_writelane_b32 v241, s5, 57
	s_cselect_b64 s[4:5], -1, 0
	v_writelane_b32 v241, s4, 58
	s_cmp_eq_u32 s64, 1
	s_movk_i32 s27, 0x80a
	v_writelane_b32 v241, s5, 59
	s_cselect_b64 s[4:5], -1, 0
	v_writelane_b32 v241, s4, 60
	s_cmp_eq_u32 s64, 0
	s_movk_i32 s28, 0x809
	v_writelane_b32 v241, s5, 61
	s_cselect_b64 s[4:5], -1, 0
	s_add_u32 s8, s68, 0xf803400
	s_addc_u32 s9, s69, 0
	v_writelane_b32 v240, s8, 0
	v_writelane_b32 v241, s4, 62
	s_mov_b32 s29, 0xbca3d70a
	v_writelane_b32 v240, s9, 1
	s_add_u32 s8, s68, 0xf803500
	s_addc_u32 s9, s69, 0
	s_abs_i32 s77, s10
	v_cvt_f32_u32_e32 v2, s77
	v_writelane_b32 v241, s5, 63
	s_mov_b64 s[4:5], 0x1400
	v_lshl_add_u64 v[164:165], v[0:1], 0, s[4:5]
	v_rcp_iflag_f32_e32 v2, v2
	s_mov_b64 s[4:5], 0x2400
	v_lshl_add_u64 v[166:167], v[0:1], 0, s[4:5]
	v_writelane_b32 v240, s8, 2
	v_mul_f32_e32 v0, 0x4f7ffffe, v2
	v_cvt_u32_f32_e32 v0, v0
	v_writelane_b32 v240, s9, 3
	s_lshr_b32 s4, s10, 1
	v_writelane_b32 v240, s4, 4
	s_sub_i32 s4, 0, s77
	v_readfirstlane_b32 s5, v0
	s_mul_i32 s4, s4, s5
	s_mul_hi_u32 s4, s5, s4
	s_add_i32 s4, s5, s4
	s_lshl_b32 s84, s10, 1
	v_writelane_b32 v240, s4, 5
	s_lshl_b32 s4, s10, 8
	v_writelane_b32 v240, s4, 6
	s_mul_i32 s4, s10, 0x600
	s_mul_hi_i32 s5, s84, 0x300
	s_ashr_i32 s85, s84, 31
	v_writelane_b32 v240, s4, 7
	s_ashr_i32 s8, s10, 31
	v_mbcnt_lo_u32_b32 v0, -1, 0
	v_writelane_b32 v240, s5, 8
	s_lshl_b64 s[4:5], s[84:85], 8
	v_writelane_b32 v240, s4, 9
	v_readlane_b32 s70, v241, 1
	v_mbcnt_hi_u32_b32 v191, -1, v0
	v_writelane_b32 v240, s5, 10
	s_lshl_b64 s[4:5], s[84:85], 11
	v_writelane_b32 v240, s4, 11
	s_mov_b32 s87, -1
	s_mov_b64 s[90:91], 0x1800
	v_writelane_b32 v240, s5, 12
	s_lshl_b64 s[4:5], s[84:85], 13
	v_writelane_b32 v240, s4, 13
	v_readlane_b32 s68, v241, 0
	v_readlane_b32 s71, v241, 2
	v_writelane_b32 v240, s5, 14
	s_lshl_b64 s[4:5], s[84:85], 12
	v_writelane_b32 v240, s4, 15
	v_readlane_b32 s69, v241, 3
	s_nop 0
	v_writelane_b32 v240, s5, 16
	s_lshl_b64 s[4:5], s[84:85], 9
	v_writelane_b32 v240, s4, 17
	s_mov_b32 s85, s8
	s_nop 0
	v_writelane_b32 v240, s5, 18
	v_writelane_b32 v240, s75, 19
	v_writelane_b32 v240, s76, 20
	v_writelane_b32 v240, s80, 21
	s_mov_b64 s[4:5], 0
	s_nop 0
	v_writelane_b32 v240, s81, 22
	v_writelane_b32 v240, s94, 23
	s_nop 1
	v_writelane_b32 v240, s95, 24
	v_writelane_b32 v240, s77, 25
	v_writelane_b32 v240, s85, 26
	s_branch .LBB0_575

; __device__ __forceinline__ void xcd_barrier(const XcdBarrier& b) {
;     ...
;             asm volatile("s_waitcnt vmcnt(0)" ::: "memory");
;         }
;     }
;     __syncthreads();
; __global__ void __launch_bounds__(512, 2) fwd_megakernel(Params p) {
;     ...
;       xcd_barrier(xb);
;     }
;   }
.LBB0_573:
	s_or_b64 exec, exec, s[4:5]
	s_waitcnt lgkmcnt(0)
	s_barrier
	s_cmp_lg_u32 s100, 0
	s_cbranch_scc1 .Lp9_h1
	s_setprio 0
	s_branch .Lp9_d

; __global__ void __launch_bounds__(512, 2) fwd_megakernel(Params p) {
;     ...
;   for (int layer = 0; layer < 4; ++layer) {
.Lp9_d:
.LBB0_574:
	v_readlane_b32 s4, v240, 27
	v_readlane_b32 s5, v240, 28
	s_add_u32 s4, s4, 1
	s_addc_u32 s5, s5, 0
	s_cmp_eq_u32 s4, 4
	s_cbranch_scc0 .LBB0_575
	s_getpc_b64 s[98:99]

; __device__ __forceinline__ int xcd_bid(int bid) { const int gpx = gridDim.x >> 3; return (bid & 7) * gpx + (bid >> 3); }
; __device__ __forceinline__ int opaque_rbid() { int t = blockIdx.x; asm volatile("" : "+s"(t)); return t; }
; __device__ __forceinline__ void xcd_barrier(const XcdBarrier& b) {
;     ...
;             asm volatile("s_waitcnt vmcnt(0)" ::: "memory");
;         }
;     }
;     __syncthreads();
; __global__ void __launch_bounds__(512, 2) fwd_megakernel(Params p) {
;     ...
;       xcd_barrier(xb);
;       {
;         const WS ws = make_ws(p);
;         const bf16_t* wb = ws.W + (size_t)j * W_PER_J;
; #pragma unroll 1
;         for (int rep = 0; rep < REP_GEMM; ++rep) {
;           gemm_stream<true, EPI_Q, 4>(ws, ws.CQ, nullptr, 512, 1 << 30, 64, wb + W_Q, 512, 1.f / 512.f, 12, 65 * 12, xcd_bid(opaque_rbid()), false);
.LBB0_685:
	s_or_b64 exec, exec, s[4:5]
	s_load_dwordx4 s[4:7], s[0:1], 0xc0
	s_waitcnt lgkmcnt(0)
	s_barrier
	s_cmp_lg_u32 s100, 0
	s_cbranch_scc1 .Lp1_h1
	s_setprio 0
	s_branch .Lp1_d

; __device__ __forceinline__ int half_id() { return __builtin_amdgcn_readfirstlane((int)(threadIdx.x >> 8)); }
; __device__ __forceinline__ int opaque_tid() { int t = threadIdx.x & 255; asm volatile("" : "+v"(t)); return t; }
; __device__ __forceinline__ int opaque_tid512() { int t = threadIdx.x; asm volatile("" : "+v"(t)); return t; }
; __device__ __forceinline__ int xcd_bid(int bid) { const int gpx = gridDim.x >> 3; return (bid & 7) * gpx + (bid >> 3); }
; __device__ __forceinline__ int opaque_rbid() { int t = blockIdx.x; asm volatile("" : "+s"(t)); return t; }
; #define smem (smem_all + half_id() * SMEM_BYTES)
;   constexpr int BMH = (TI == 5) ? 129 : 128;
;   constexpr int ASTG = 16384;
;   unsigned char* As = smem;
;   unsigned char* Bs = smem_all + 2 * ASTG;
;   float* rsl = (float*)(smem + 65536);
;   int xbase = 66048;
;   asm volatile("" : "+v"(xbase));
;   unsigned char* Ax0 = smem + xbase;
;   const int tid = opaque_tid(), lane = tid & 63, w = tid >> 6, wm = w >> 1, wn = w & 1, lr = lane & 15, lq = lane >> 4;
;   const int tid5 = opaque_tid512(), hh = half_id();
;   const int G = gridDim.x;
;   const int nk = K >> 6;
;   if (bid < ntiles) {
;     const int my_tiles = (ntiles - 1 - bid) / G + 1;
;     const int last_id = bid + (my_tiles - 1) * G;
;     const int S = my_tiles * nk;
; __global__ void __launch_bounds__(512, 2) fwd_megakernel(Params p) {
;     ...
;           gemm_stream<true, EPI_Q, 4>(ws, ws.CQ, nullptr, 512, 1 << 30, 64, wb + W_Q, 512, 1.f / 512.f, 12, 65 * 12, xcd_bid(opaque_rbid()), false);
.Lp1_d:
	s_lshl_b64 s[50:51], s[48:49], 1
	s_waitcnt vmcnt(4)
	v_mov_b32_e32 v0, s6
	v_mov_b32_e32 v1, s7
	v_readfirstlane_b32 s9, v175
	v_readfirstlane_b32 s40, v0
	v_readfirstlane_b32 s41, v1
	v_mov_b32_e32 v0, s4
	v_mov_b32_e32 v1, s5
	v_mov_b32_e32 v13, v186
	v_readfirstlane_b32 s4, v0
	v_readfirstlane_b32 s5, v1
	s_add_u32 s30, s4, s50
	s_mov_b32 s4, s68
	s_addc_u32 s31, s5, s51
	s_and_b32 s5, s4, 7
	s_mul_i32 s5, s5, s75
	s_ashr_i32 s4, s4, 3
	s_add_i32 s34, s5, s4
	v_mov_b32_e32 v0, 0x10200
	v_mov_b32_e32 v51, v175
	s_cmpk_lt_i32 s34, 0x30c
	s_cbranch_scc0 .LBB0_733
	s_sub_i32 s4, 0x30b, s34
	v_readlane_b32 s5, v240, 5
	s_mul_hi_u32 s5, s4, s5
	s_mul_i32 s6, s5, s77
	s_sub_i32 s4, s4, s6
	s_add_i32 s6, s5, 1
	s_sub_i32 s7, s4, s77
	s_cmp_ge_u32 s4, s77
	s_cselect_b32 s5, s6, s5
	s_cselect_b32 s4, s7, s4
	s_add_i32 s6, s5, 1
	s_cmp_ge_u32 s4, s77
	s_cselect_b32 s4, s6, s5
	s_xor_b32 s4, s4, s85
	s_sub_i32 s8, s4, s85
	s_load_dwordx2 s[4:5], s[0:1], 0x110
	s_waitcnt lgkmcnt(0)
	s_mul_i32 s35, s8, s4
	s_add_i32 s35, s35, s34
	s_min_i32 s10, s34, s35
	s_cmpk_gt_i32 s10, 0x2ff
	s_cselect_b64 s[12:13], -1, 0
	s_mov_b64 s[4:5], -1
	s_and_b64 vcc, exec, s[12:13]
	s_cbranch_vccz .LBB0_688
	s_add_i32 s37, s10, 0xfffffd00
	s_mov_b64 s[4:5], 0

; __device__ __forceinline__ int opaque_bid() { int t = blockIdx.x * 2 + half_id(); asm volatile("" : "+s"(t)); return t; }
; __global__ void __launch_bounds__(512, 2) fwd_megakernel(Params p) {
;     ...
;         const WS ws = make_ws(p);
; #pragma unroll 1
;         for (int rep = 0; rep < REP_ATTN; ++rep)
; #pragma unroll 1
;         for (int r = 0, b0 = opaque_bid(); r * NVB < 17 * 128; ++r) {
;           const int u = r * NVB + ((r & 1) ? NVB - 1 - b0 : b0);
.Lp2_d:
	s_mov_b32 s65, 0
	s_mov_b64 s[10:11], s[6:7]
	s_waitcnt vmcnt(4)
	v_mov_b32_e32 v0, s10
	v_mov_b32_e32 v1, s11
	s_mov_b64 s[8:9], s[4:5]
	s_nop 0
	v_readfirstlane_b32 s4, v0
	v_readfirstlane_b32 s5, v1
	s_add_u32 s52, s4, 0x4080000
	s_addc_u32 s53, s5, 0
	s_add_u32 s54, s4, 0x5ab4000
	s_addc_u32 s55, s5, 0
	s_add_u32 s56, s4, 0x7af4000
	s_addc_u32 s57, s5, 0
	s_add_u32 s58, s4, 0x7bf6000
	s_addc_u32 s59, s5, 0
	s_add_u32 s60, s4, 0xac56000
	s_addc_u32 s61, s5, 0
	s_add_u32 s30, s4, 0xcc96000
	v_readfirstlane_b32 s4, v175
	s_addc_u32 s31, s5, 0
	s_lshr_b32 s4, s4, 8
	v_mov_b32_e32 v0, s8
	v_mov_b32_e32 v1, s9
	s_add_i32 s49, s4, s69
	s_not_b32 s4, s49
	s_add_i32 s64, s84, s4
	s_mov_b32 s4, 0
	s_branch .LBB0_837

; __device__ __forceinline__ void rem_tile(int pos, int& mt, int& nt) { if (pos < 65) { mt = pos; nt = 40; } else { mt = 64; nt = pos - 65; } }
;     ...
;     auto issue = [&](u32x4 (&ra)[4], u32x4 (&rb)[2], u32x4& rx) {
;       const int idc = l_id < last_id ? l_id : last_id;
;       int mt, nt; if (TMAP == 1) rem_tile(idc, mt, nt); else tile_of(idc, ntn, mt, nt);
;       const bf16_t* A = (l_kt < ktsplit) ? A0 : A1;
;       const int kk = (l_kt < ktsplit) ? l_kt : l_kt - ktsplit;
;       const int arow = mt * 2 * BMH + hh * BMH + srow;
;       const bf16_t* akb = A + kk * kstride + (tid & 7) * 8;
;       const bf16_t* wp = W + (size_t)(nt * 128 + wrow) * K + l_kt * 64 + (tid5 & 7) * 8;
; #pragma unroll
;       for (int i = 0; i < 4; ++i) {
;         int r = arow + 32 * i; r = r < M_ ? r : M_ - 1;
;         ra[i] = *(const u32x4*)(akb + (size_t)r * lda);
;       }
; #pragma unroll
;       for (int i = 0; i < 2; ++i) rb[i] = *(const u32x4*)(wp + (size_t)i * 64 * K);
;       if (TI == 5) rx = *(const u32x4*)(akb + (size_t)(arow - srow + 128) * lda);
;       if (++l_kt == nk) { l_kt = 0; l_id += G; }
;     };
;     auto store = [&](const u32x4 (&ra)[4], const u32x4 (&rb)[2], const u32x4& rx, int buf) {
; #pragma unroll
;       for (int i = 0; i < 4; ++i) {
;         if (RS) ss[i] += sumsq8(__builtin_bit_cast(bf16x8, ra[i]));
;         *(u32x4*)(As + buf * ASTG + i * 4096 + soff) = ra[i];
;       }
; #pragma unroll
;       for (int i = 0; i < 2; ++i) *(u32x4*)(Bs + buf * 16384 + i * 8192 + woff) = rb[i];
;       if (TI == 5) {
;         if (RS) ss[4] += sumsq8(__builtin_bit_cast(bf16x8, rx));
;         if (srow == 0) *(u32x4*)(Ax0 + buf * 128 + ((tid & 7) << 4)) = rx;
;     ...
;     issue(ra0, rb0, rx0);
;     issue(ra1, rb1, rx1);
;     store(ra0, rb0, rx0, 0);
.Lp3_d:
	s_waitcnt vmcnt(0)
	v_mov_b32_e32 v33, 0x10200
	v_mov_b32_e32 v0, s6
	v_mov_b32_e32 v1, s7
	s_mov_b32 s6, s68
	v_readfirstlane_b32 s44, v0
	v_readfirstlane_b32 s45, v1
	v_mov_b32_e32 v0, s4
	v_mov_b32_e32 v1, s5
	s_and_b32 s7, s6, 7
	s_mul_i32 s7, s7, s75
	s_ashr_i32 s6, s6, 3
	s_add_i32 s12, s7, s6
	v_readfirstlane_b32 s4, v0
	v_readfirstlane_b32 s5, v1
	v_readfirstlane_b32 s6, v175
	v_mov_b32_e32 v13, v186
	v_mov_b32_e32 v32, v175
	s_cmpk_lt_i32 s12, 0x200
	s_cbranch_scc0 .LBB0_983
	s_add_u32 s46, s44, 0x7bf6000
	s_addc_u32 s47, s45, 0
	s_add_u32 s4, s4, s50
	s_addc_u32 s5, s5, s51
	s_add_u32 s50, s4, 0x1480000
	s_addc_u32 s51, s5, 0
	s_sub_i32 s4, 0x1ff, s12
	v_readlane_b32 s5, v240, 5
	s_mul_hi_u32 s5, s4, s5
	s_lshr_b32 s9, s6, 8
	s_mul_i32 s6, s5, s77
	s_sub_i32 s4, s4, s6
	s_add_i32 s6, s5, 1
	s_sub_i32 s7, s4, s77
	s_cmp_ge_u32 s4, s77
	s_cselect_b32 s5, s6, s5
	s_cselect_b32 s4, s7, s4
	s_add_i32 s6, s5, 1
	s_cmp_ge_u32 s4, s77
	s_cselect_b32 s4, s6, s5
	s_xor_b32 s4, s4, s85
	s_sub_i32 s8, s4, s85
	s_load_dwordx2 s[4:5], s[0:1], 0x110
	v_ashrrev_i32_e32 v173, 3, v13
	s_mul_i32 s30, s9, 0x81
	v_add_u32_e32 v176, s30, v173
	v_lshlrev_b32_e32 v0, 3, v13
	s_waitcnt lgkmcnt(0)
	s_mul_i32 s13, s8, s4
	s_add_i32 s13, s13, s12
	s_min_i32 s4, s12, s13
	s_ashr_i32 s5, s4, 31
	s_lshr_b32 s5, s5, 26
	s_add_i32 s5, s4, s5
	s_ashr_i32 s5, s5, 6
	s_lshl_b32 s6, s5, 3
	s_and_b32 s7, s4, 7
	s_or_b32 s6, s6, s7
	s_mulk_i32 s6, 0x102
	v_add_u32_e32 v6, s6, v176
	v_and_b32_e32 v0, 56, v0
	s_lshl_b32 s5, s5, 10
	s_lshl_b32 s4, s4, 4
	v_lshlrev_b32_e32 v168, 1, v0
	v_mov_b32_e32 v169, v12
	s_sub_i32 s4, s4, s5
	v_min_i32_e32 v4, 0x405f, v6
	v_ashrrev_i32_e32 v174, 3, v32
	s_waitcnt vmcnt(3)
	v_lshl_add_u64 v[14:15], s[46:47], 0, v[168:169]
	s_and_b32 s4, s4, 0xffffff80
	v_lshlrev_b32_e32 v2, 3, v32
	s_waitcnt vmcnt(2)
	v_min_i32_e32 v8, 0x407f, v6
	v_add_u32_e32 v9, 32, v4
	v_add_u32_e32 v0, s4, v174
	v_and_b32_e32 v7, 56, v2
	v_mad_i64_i32 v[2:3], s[4:5], v8, s83, v[14:15]
	v_mad_i64_i32 v[4:5], s[4:5], v9, s83, v[14:15]
	global_load_dwordx4 v[34:37], v[2:3], off
	global_load_dwordx4 v[38:41], v[4:5], off
	v_min_i32_e32 v2, 0x403f, v6
	v_min_i32_e32 v4, 0x401f, v6
	v_ashrrev_i32_e32 v1, 31, v0
	v_add_u32_e32 v10, 64, v2
	v_add_u32_e32 v11, 0x60, v4
	v_mad_i64_i32 v[2:3], s[4:5], v10, s83, v[14:15]
	v_mad_i64_i32 v[4:5], s[4:5], v11, s83, v[14:15]
	v_lshlrev_b64 v[0:1], 11, v[0:1]
	v_lshl_add_u64 v[0:1], s[50:51], 0, v[0:1]
	v_lshlrev_b32_e32 v170, 1, v7
	v_mov_b32_e32 v171, v12
	s_add_i32 s4, s6, s30
	s_waitcnt vmcnt(2)
	v_lshl_add_u64 v[20:21], v[0:1], 0, v[170:171]
	s_addk_i32 s4, 0x80
	v_lshl_add_u64 v[0:1], s[44:45], 0, v[168:169]
	s_mov_b64 s[6:7], 0x7bf60c0
	v_add_co_u32_e32 v24, vcc, s2, v20
	s_mul_hi_i32 s5, s4, 0x600
	s_mulk_i32 s4, 0x600
	v_lshl_add_u64 v[28:29], v[0:1], 0, s[6:7]
	global_load_dwordx4 v[42:45], v[2:3], off
	global_load_dwordx4 v[46:49], v[4:5], off
	v_addc_co_u32_e32 v25, vcc, 0, v21, vcc
	v_mad_i64_i32 v[0:1], s[6:7], v8, s83, v[28:29]
	v_mad_i64_i32 v[4:5], s[6:7], v9, s83, v[28:29]
	v_mad_i64_i32 v[8:9], s[6:7], v10, s83, v[28:29]
	v_mad_i64_i32 v[16:17], s[6:7], v11, s83, v[28:29]
	v_lshl_add_u64 v[28:29], s[4:5], 1, v[28:29]
	global_load_dwordx4 v[0:3], v[0:1], off
	s_nop 0
	global_load_dwordx4 v[4:7], v[4:5], off
	s_nop 0
	global_load_dwordx4 v[8:11], v[8:9], off
	s_nop 0
	global_load_dwordx4 v[16:19], v[16:17], off
	s_nop 0
	global_load_dwordx4 v[50:53], v[20:21], off
	s_nop 0
	global_load_dwordx4 v[20:23], v[20:21], off offset:128
	s_nop 0
	global_load_dwordx4 v[54:57], v[24:25], off
	s_nop 0
	global_load_dwordx4 v[24:27], v[24:25], off offset:128
	v_xor_b32_e32 v59, v173, v13
	global_load_dwordx4 v[28:31], v[28:29], off
	v_lshlrev_b32_e32 v58, 7, v173
	v_lshlrev_b32_e32 v59, 4, v59
	s_movk_i32 s3, 0x70
	v_xor_b32_e32 v32, v174, v32
	s_mul_i32 s9, s9, 0x12800
	v_and_or_b32 v58, v59, s3, v58
	v_lshlrev_b32_e32 v59, 7, v174
	v_lshlrev_b32_e32 v32, 4, v32
	v_add_u32_e32 v33, s9, v33
	v_and_or_b32 v177, v32, s3, v59
	v_add_u32_e32 v178, s9, v58
	v_cmp_gt_u32_e64 s[38:39], 8, v13
	s_waitcnt vmcnt(12)
	ds_write_b128 v178, v[34:37]
	s_waitcnt vmcnt(11)
	ds_write_b128 v178, v[38:41] offset:4096
	s_waitcnt vmcnt(10)
	ds_write_b128 v178, v[42:45] offset:8192
	s_waitcnt vmcnt(9)
	ds_write_b128 v178, v[46:49] offset:12288
	s_waitcnt vmcnt(4)
	ds_write_b128 v177, v[50:53] offset:32768
	s_waitcnt vmcnt(2)
	ds_write_b128 v177, v[54:57] offset:40960
	s_and_saveexec_b64 s[6:7], s[38:39]
	s_cbranch_execz .LBB0_936
	v_lshl_add_u64 v[14:15], s[4:5], 1, v[14:15]
	global_load_dwordx4 v[34:37], v[14:15], off
	v_lshl_add_u32 v14, v13, 4, v33
	s_waitcnt vmcnt(0)
	ds_write_b128 v14, v[34:37]

; __device__ __forceinline__ int half_id() { return __builtin_amdgcn_readfirstlane((int)(threadIdx.x >> 8)); }
; __device__ __forceinline__ int opaque_tid512() { int t = threadIdx.x; asm volatile("" : "+v"(t)); return t; }
; template <int EPI>
; __device__ __forceinline__ void gemm_wide(const WS& ws, const bf16_t* A, int lda, const bf16_t* __restrict__ W, int K, float invK,
;                                           int ntn, int ntiles, int bid) {
;     ...
;   const int tid5 = opaque_tid512(), hh = half_id();
;   const int G = gridDim.x;
;   const int nk = K >> 6;
;   if (bid < ntiles) {
;     const int my_tiles = (ntiles - 1 - bid) / G + 1;
;     const int last_id = bid + (my_tiles - 1) * G;
;     const int S = my_tiles * nk;
;     f32x4 accA[4][4], accB[4][4];
; #pragma unroll
;     for (int a = 0; a < 4; ++a)
; #pragma unroll
;       for (int b = 0; b < 4; ++b) { accA[a][b] = (f32x4){0.f, 0.f, 0.f, 0.f}; accB[a][b] = (f32x4){0.f, 0.f, 0.f, 0.f}; }
;     u32x4 ra[4], rb[4];
;     float ss[4] = {0.f, 0.f, 0.f, 0.f};
;     int l_id = bid, l_kt = 0, c_id = bid, c_kt = 0, st_kt = 0;
;     const int srow = tid >> 3;
;     const int soff = srow * 128 + (((tid & 7) ^ (srow & 7)) << 4);
;     const int wrow = tid5 >> 3;
;     const int woff = wrow * 128 + (((tid5 & 7) ^ (wrow & 7)) << 4);
;     auto issue = [&]() {
;       const int idc = l_id < last_id ? l_id : last_id;
;       int mt, nt; tile_of(idc, ntn, mt, nt);
;       const int arow = mt * 256 + hh * 128 + srow;
;       const bf16_t* akb = A + l_kt * 64 + (tid & 7) * 8;
;       const bf16_t* wp = W + (size_t)(nt * 256 + wrow) * K + l_kt * 64 + (tid5 & 7) * 8;
; #pragma unroll
;       for (int i = 0; i < 4; ++i) {
;         int r = arow + 32 * i; r = r < M_ ? r : M_ - 1;
;         ra[i] = *(const u32x4*)(akb + (size_t)r * lda);
;         rb[i] = *(const u32x4*)(wp + (size_t)i * 64 * K);
;       }
;       if (++l_kt == nk) { l_kt = 0; l_id += G; }
;     };
;     ...
;     issue();
;     store(0);
;     __syncthreads();
.Lp4_d:
	s_mov_b64 s[4:5], 0
.LBB0_1033:
	s_and_b64 vcc, exec, s[4:5]
	s_cbranch_vccz .LBB0_574
	s_load_dwordx4 s[4:7], s[0:1], 0xc0
	s_mov_b32 s49, s93
	v_mov_b32_e32 v13, v186
	s_waitcnt vmcnt(0)
	v_mov_b32_e32 v19, v175
	s_waitcnt lgkmcnt(0)
	v_mov_b32_e32 v0, s6
	v_mov_b32_e32 v1, s7
	s_nop 0
	v_readfirstlane_b32 s58, v0
	v_readfirstlane_b32 s59, v1
	s_add_u32 s42, s58, 0x4284000
	s_addc_u32 s43, s59, 0
	s_add_u32 s44, s58, 0x62c4000
	s_addc_u32 s45, s59, 0
	s_add_u32 s46, s58, 0x8304000
	s_addc_u32 s47, s59, 0
	s_add_u32 s50, s58, 0x9324000
	s_addc_u32 s51, s59, 0
	s_add_u32 s52, s58, 0xa344000
	s_addc_u32 s53, s59, 0
	s_add_u32 s54, s58, 0xc384000
	s_addc_u32 s55, s59, 0
	s_add_u32 s56, s58, 0xe3c4000
	v_mov_b32_e32 v0, s4
	v_mov_b32_e32 v1, s5
	s_addc_u32 s57, s59, 0
	s_lshl_b64 s[4:5], s[48:49], 1
	v_readfirstlane_b32 s30, v0
	s_add_u32 s48, s30, s4
	v_writelane_b32 v240, s4, 30
	v_readfirstlane_b32 s31, v1
	s_addc_u32 s49, s31, s5
	v_writelane_b32 v240, s5, 31
	s_mov_b32 s4, s68
	s_and_b32 s5, s4, 7
	s_mul_i32 s5, s5, s75
	s_ashr_i32 s4, s4, 3
	s_add_i32 s62, s5, s4
	v_readfirstlane_b32 s4, v175
	s_cmpk_lt_i32 s62, 0x500
	s_cbranch_scc0 .LBB0_1104
	s_sub_i32 s6, 0x4ff, s62
	v_readlane_b32 s7, v240, 5
	s_mul_hi_u32 s7, s6, s7
	s_mul_i32 s8, s7, s77
	s_lshr_b32 s5, s4, 8
	s_sub_i32 s6, s6, s8
	s_lshl_b32 s4, s5, 15
	s_add_i32 s8, s7, 1
	s_sub_i32 s9, s6, s77
	s_cmp_ge_u32 s6, s77
	s_cselect_b32 s7, s8, s7
	s_cselect_b32 s6, s9, s6
	s_add_i32 s8, s7, 1
	s_cmp_ge_u32 s6, s77
	s_cselect_b32 s6, s8, s7
	s_load_dwordx2 s[8:9], s[0:1], 0x110
	s_xor_b32 s6, s6, s85
	s_sub_i32 s6, s6, s85
	v_ashrrev_i32_e32 v18, 3, v13
	s_lshl_b32 s64, s5, 7
	s_waitcnt lgkmcnt(0)
	s_mul_i32 s63, s6, s8
	s_add_i32 s63, s63, s62
	s_min_i32 s7, s62, s63
	s_mul_hi_i32 s8, s7, 0x66666667
	s_lshr_b32 s9, s8, 31
	s_ashr_i32 s8, s8, 6
	s_add_i32 s8, s8, s9
	s_mul_i32 s9, s8, 0xffffff60
	s_add_i32 s9, s9, s7
	s_lshl_b32 s7, s7, 8
	s_lshl_b32 s8, s8, 11
	s_and_b32 s7, s7, 0x700
	v_add_u32_e32 v202, s64, v18
	s_or_b32 s7, s8, s7
	v_add_u32_e32 v16, s7, v202
	v_lshlrev_b32_e32 v0, 4, v13
	s_lshl_b32 s7, s9, 5
	v_lshlrev_b32_e32 v2, 3, v19
	v_ashrrev_i32_e32 v201, 3, v19
	v_and_b32_e32 v0, 0x70, v0
	v_mov_b32_e32 v1, v12
	s_and_b32 s7, s7, 0xffffff00
	v_and_b32_e32 v2, 56, v2
	v_lshl_add_u64 v[162:163], s[58:59], 0, v[0:1]
	v_add_u32_e32 v0, s7, v201
	v_lshlrev_b32_e32 v168, 1, v2
	v_min_i32_e32 v2, 0x405f, v16
	v_ashrrev_i32_e32 v1, 31, v0
	v_ashrrev_i32_e32 v3, 31, v2
	v_lshlrev_b64 v[0:1], 11, v[0:1]
	v_lshlrev_b64 v[2:3], 11, v[2:3]
	v_lshl_add_u64 v[0:1], s[48:49], 0, v[0:1]
	v_mov_b32_e32 v169, v12
	v_lshl_add_u64 v[2:3], v[162:163], 0, v[2:3]
	v_lshl_add_u64 v[32:33], v[0:1], 0, v[168:169]
	v_min_i32_e32 v0, 0x407f, v16
	v_add_co_u32_e32 v4, vcc, s82, v2
	v_ashrrev_i32_e32 v1, 31, v0
	s_nop 0
	v_addc_co_u32_e32 v5, vcc, 0, v3, vcc
	s_mov_b32 s3, 0x20000
	v_lshlrev_b64 v[0:1], 11, v[0:1]
	v_add_co_u32_e32 v8, vcc, s3, v32
	v_lshl_add_u64 v[0:1], v[162:163], 0, v[0:1]
	s_nop 0
	v_addc_co_u32_e32 v9, vcc, 0, v33, vcc
	global_load_dwordx4 v[20:23], v[32:33], off
	s_nop 0
	global_load_dwordx4 v[0:3], v[0:1], off
	s_nop 0
	global_load_dwordx4 v[4:7], v[4:5], off
	v_xor_b32_e32 v37, v18, v13
	global_load_dwordx4 v[24:27], v[8:9], off
	v_min_i32_e32 v8, 0x403f, v16
	v_ashrrev_i32_e32 v9, 31, v8
	v_lshlrev_b64 v[8:9], 11, v[8:9]
	v_lshl_add_u64 v[8:9], v[162:163], 0, v[8:9]
	v_add_co_u32_e32 v8, vcc, s3, v8
	s_mov_b32 s3, 0x40000
	s_nop 0
	v_addc_co_u32_e32 v9, vcc, 0, v9, vcc
	v_add_co_u32_e32 v14, vcc, s3, v32
	s_mov_b32 s3, 0x30000
	s_nop 0
	v_addc_co_u32_e32 v15, vcc, 0, v33, vcc
	global_load_dwordx4 v[28:31], v[14:15], off
	v_min_i32_e32 v14, 0x401f, v16
	v_ashrrev_i32_e32 v15, 31, v14
	v_lshlrev_b64 v[14:15], 11, v[14:15]
	v_lshl_add_u64 v[14:15], v[162:163], 0, v[14:15]
	v_add_co_u32_e32 v14, vcc, s3, v14
	s_mov_b32 s3, 0x60000
	s_nop 0
	v_addc_co_u32_e32 v15, vcc, 0, v15, vcc
	v_add_co_u32_e32 v32, vcc, s3, v32
	global_load_dwordx4 v[8:11], v[8:9], off
	s_nop 0
	v_addc_co_u32_e32 v33, vcc, 0, v33, vcc
	global_load_dwordx4 v[14:17], v[14:15], off
	v_lshlrev_b32_e32 v36, 7, v18
	global_load_dwordx4 v[32:35], v[32:33], off
	v_lshlrev_b32_e32 v37, 4, v37
	s_movk_i32 s3, 0x70
	v_xor_b32_e32 v19, v201, v19
	v_and_or_b32 v36, v37, s3, v36
	v_lshlrev_b32_e32 v37, 7, v201
	v_lshlrev_b32_e32 v19, 4, v19
	v_and_or_b32 v19, v19, s3, v37
	s_lshl_b32 s34, s6, 4
	v_add_u32_e32 v203, s4, v36
	v_add_u32_e32 v204, 0x10000, v19
	s_add_i32 s34, s34, 16
	s_mov_b32 s2, 0x20000
	s_cmp_lt_i32 s34, 1
	s_waitcnt vmcnt(6)
	ds_write_b128 v203, v[0:3]
	ds_write_b128 v204, v[20:23]
	s_waitcnt vmcnt(5)
	ds_write_b128 v203, v[4:7] offset:4096
	v_add_u32_e32 v20, 0x12000, v19
	s_waitcnt vmcnt(4)
	ds_write_b128 v20, v[24:27]
	s_waitcnt vmcnt(2)
	ds_write_b128 v203, v[8:11] offset:8192
	v_add_u32_e32 v20, 0x14000, v19
	v_add_u32_e32 v19, 0x16000, v19
	ds_write_b128 v20, v[28:31]
	s_waitcnt vmcnt(1)
	ds_write_b128 v203, v[14:17] offset:12288
	s_waitcnt vmcnt(0)
	ds_write_b128 v19, v[32:35]
	s_waitcnt lgkmcnt(0)
	s_barrier
	s_cbranch_scc1 .LBB0_1104
; template <int EPI>
; __device__ __forceinline__ void gemm_wide(const WS& ws, const bf16_t* A, int lda, const bf16_t* __restrict__ W, int K, float invK,
;                                           int ntn, int ntiles, int bid) {
;     ...
;     f32x4 accA[4][4], accB[4][4];
; #pragma unroll
;     for (int a = 0; a < 4; ++a)
; #pragma unroll
;       for (int b = 0; b < 4; ++b) { accA[a][b] = (f32x4){0.f, 0.f, 0.f, 0.f}; accB[a][b] = (f32x4){0.f, 0.f, 0.f, 0.f}; }
;     u32x4 ra[4], rb[4];
;     float ss[4] = {0.f, 0.f, 0.f, 0.f};
;     int l_id = bid, l_kt = 0, c_id = bid, c_kt = 0, st_kt = 0;
;     const int srow = tid >> 3;
;     const int soff = srow * 128 + (((tid & 7) ^ (srow & 7)) << 4);
;     const int wrow = tid5 >> 3;
;     const int woff = wrow * 128 + (((tid5 & 7) ^ (wrow & 7)) << 4);
;     auto issue = [&]() {
;       const int idc = l_id < last_id ? l_id : last_id;
;       int mt, nt; tile_of(idc, ntn, mt, nt);
;       const int arow = mt * 256 + hh * 128 + srow;
;       const bf16_t* akb = A + l_kt * 64 + (tid & 7) * 8;
;       const bf16_t* wp = W + (size_t)(nt * 256 + wrow) * K + l_kt * 64 + (tid5 & 7) * 8;
; #pragma unroll
;       for (int i = 0; i < 4; ++i) {
;         int r = arow + 32 * i; r = r < M_ ? r : M_ - 1;
;         ra[i] = *(const u32x4*)(akb + (size_t)r * lda);
;         rb[i] = *(const u32x4*)(wp + (size_t)i * 64 * K);
;       }
;       if (++l_kt == nk) { l_kt = 0; l_id += G; }
;     };
;     auto store = [&](int buf) {
; #pragma unroll
;       for (int i = 0; i < 4; ++i) {
;         ss[i] += sumsq8(__builtin_bit_cast(bf16x8, ra[i]));
;         *(u32x4*)(As + buf * 16384 + i * 4096 + soff) = ra[i];
;         *(u32x4*)(Bs + buf * 32768 + i * 8192 + woff) = rb[i];
;       }
;       if (++st_kt == nk) {
;         st_kt = 0;
; #pragma unroll
;         for (int i = 0; i < 4; ++i) {
;           float t = ss[i];
;           t += __shfl_xor(t, 1); t += __shfl_xor(t, 2); t += __shfl_xor(t, 4);
;           if ((tid & 7) == 0) rsl[srow + 32 * i] = rsqrtf(t * invK + EPS_);
;           ss[i] = 0.f;
;         }
;       }
;     };
;     auto compute = [&](int buf) {
;       const unsigned char* Ab = As + buf * 16384 + (wn * 64 + lr) * 128;
;       const unsigned char* Bb = Bs + buf * 32768 + (wm * 64 + lr) * 128;
; #pragma unroll
;       for (int ks = 0; ks < 2; ++ks) {
;         if (ks == 1) __builtin_amdgcn_sched_barrier(0);
	v_and_b32_e32 v22, 0xffff0000, v14
	v_and_b32_e32 v23, 0xffff0000, v8
	v_lshlrev_b32_e32 v20, 16, v14
	v_lshlrev_b32_e32 v21, 16, v8
	v_and_b32_e32 v25, 0xffff0000, v11
	v_lshlrev_b32_e32 v27, 16, v11
	v_and_b32_e32 v29, 0xffff0000, v10
	v_and_b32_e32 v28, 0xffff0000, v16
	v_lshlrev_b32_e32 v11, 16, v10
	v_lshlrev_b32_e32 v10, 16, v16
	v_and_b32_e32 v16, 0xffff0000, v15
	v_lshlrev_b32_e32 v8, 16, v15
	v_pk_mul_f32 v[14:15], v[22:23], v[22:23]
	v_and_b32_e32 v24, 0xffff0000, v17
	v_lshlrev_b32_e32 v26, 16, v17
	v_and_b32_e32 v17, 0xffff0000, v9
	v_lshlrev_b32_e32 v9, 16, v9
	v_pk_fma_f32 v[14:15], v[20:21], v[20:21], v[14:15]
	v_and_b32_e32 v21, 0xffff0000, v2
	v_pk_fma_f32 v[8:9], v[8:9], v[8:9], v[14:15]
	v_and_b32_e32 v15, 0xffff0000, v3
	v_pk_fma_f32 v[8:9], v[16:17], v[16:17], v[8:9]
	v_lshlrev_b32_e32 v17, 16, v3
	v_pk_fma_f32 v[8:9], v[10:11], v[10:11], v[8:9]
	v_and_b32_e32 v10, 0xffff0000, v4
	v_pk_fma_f32 v[8:9], v[28:29], v[28:29], v[8:9]
	v_and_b32_e32 v11, 0xffff0000, v0
	v_pk_fma_f32 v[8:9], v[26:27], v[26:27], v[8:9]
	v_and_b32_e32 v20, 0xffff0000, v6
	v_pk_fma_f32 v[170:171], v[24:25], v[24:25], v[8:9]
	v_lshlrev_b32_e32 v8, 16, v4
	v_lshlrev_b32_e32 v9, 16, v0
	v_lshlrev_b32_e32 v3, 16, v2
	v_lshlrev_b32_e32 v2, 16, v6
	v_and_b32_e32 v6, 0xffff0000, v5
	v_lshlrev_b32_e32 v0, 16, v5
	v_pk_mul_f32 v[4:5], v[10:11], v[10:11]
	v_and_b32_e32 v14, 0xffff0000, v7
	v_lshlrev_b32_e32 v16, 16, v7
	v_and_b32_e32 v7, 0xffff0000, v1
	v_lshlrev_b32_e32 v1, 16, v1
	v_pk_fma_f32 v[4:5], v[8:9], v[8:9], v[4:5]
	v_bfe_u32 v30, v13, 6, 1
	v_pk_fma_f32 v[0:1], v[0:1], v[0:1], v[4:5]
	v_and_b32_e32 v31, 15, v13
	v_pk_fma_f32 v[0:1], v[6:7], v[6:7], v[0:1]
	v_ashrrev_i32_e32 v19, 7, v13
	v_pk_fma_f32 v[0:1], v[2:3], v[2:3], v[0:1]
	v_lshrrev_b32_e32 v32, 4, v13
	v_pk_fma_f32 v[0:1], v[20:21], v[20:21], v[0:1]
	s_lshl_b32 s5, s5, 10
	v_pk_fma_f32 v[0:1], v[16:17], v[16:17], v[0:1]
	v_bfe_u32 v33, v13, 4, 2
	v_pk_fma_f32 v[176:177], v[14:15], v[14:15], v[0:1]
	v_lshlrev_b32_e32 v0, 13, v30
	v_lshlrev_b32_e32 v1, 7, v31
	v_add3_u32 v205, s4, v0, v1
	v_lshl_or_b32 v0, v19, 13, v1
	v_add_u32_e32 v206, 0x10000, v0
	v_and_b32_e32 v0, 7, v13
	v_bitop3_b32 v1, v32, v0, 3 bitop3:0x6c
	s_add_i32 s5, s5, 0x20000
	v_lshlrev_b32_e32 v207, 4, v1
	v_bitop3_b32 v1, v33, v0, 4 bitop3:0x36
	v_lshl_or_b32 v209, v30, 6, v31
	v_lshlrev_b32_e32 v172, 6, v19
	s_movk_i32 s2, 0x80
	v_mov_b32_e32 v66, 0
	v_lshlrev_b32_e32 v208, 4, v1
	v_lshl_or_b32 v210, v209, 2, s5
	v_ashrrev_i32_e32 v173, 31, v172
	v_lshlrev_b32_e32 v174, 2, v33
	v_cmp_gt_u32_e64 s[38:39], s2, v13
	s_mov_b32 s35, 0
	v_cmp_eq_u32_e64 s[40:41], 0, v0
	v_lshl_add_u32 v211, v18, 2, s5
	s_mov_b32 s65, 1
	s_mov_b32 s6, 0
	s_mov_b32 s66, s62
	s_mov_b32 s67, 1
	v_mov_b32_e32 v67, v66
	v_mov_b32_e32 v68, v66
	v_mov_b32_e32 v69, v66
	v_mov_b32_e32 v70, v66
	v_mov_b32_e32 v71, v66
	v_mov_b32_e32 v72, v66
	v_mov_b32_e32 v73, v66
	v_mov_b32_e32 v74, v66
	v_mov_b32_e32 v75, v66
	v_mov_b32_e32 v76, v66
	v_mov_b32_e32 v77, v66
	v_mov_b32_e32 v78, v66
	v_mov_b32_e32 v79, v66
	v_mov_b32_e32 v80, v66
	v_mov_b32_e32 v81, v66
	v_mov_b32_e32 v82, v66
	v_mov_b32_e32 v83, v66
	v_mov_b32_e32 v84, v66
	v_mov_b32_e32 v85, v66
	v_mov_b32_e32 v86, v66
	v_mov_b32_e32 v87, v66
	v_mov_b32_e32 v88, v66
	v_mov_b32_e32 v89, v66
	v_mov_b32_e32 v90, v66
	v_mov_b32_e32 v91, v66
	v_mov_b32_e32 v92, v66
	v_mov_b32_e32 v93, v66
	v_mov_b32_e32 v94, v66
	v_mov_b32_e32 v95, v66
	v_mov_b32_e32 v96, v66
	v_mov_b32_e32 v97, v66
	v_mov_b32_e32 v114, v66
	v_mov_b32_e32 v115, v66
	v_mov_b32_e32 v116, v66
	v_mov_b32_e32 v117, v66
	v_mov_b32_e32 v130, v66
	v_mov_b32_e32 v131, v66
	v_mov_b32_e32 v132, v66
	v_mov_b32_e32 v133, v66
	v_mov_b32_e32 v138, v66
	v_mov_b32_e32 v139, v66
	v_mov_b32_e32 v140, v66
	v_mov_b32_e32 v141, v66
	v_mov_b32_e32 v142, v66
	v_mov_b32_e32 v143, v66
	v_mov_b32_e32 v144, v66
	v_mov_b32_e32 v145, v66
	v_mov_b32_e32 v146, v66
	v_mov_b32_e32 v147, v66
	v_mov_b32_e32 v148, v66
	v_mov_b32_e32 v149, v66
	v_mov_b32_e32 v150, v66
	v_mov_b32_e32 v151, v66
	v_mov_b32_e32 v152, v66
	v_mov_b32_e32 v153, v66
	v_mov_b32_e32 v154, v66
	v_mov_b32_e32 v155, v66
	v_mov_b32_e32 v156, v66
	v_mov_b32_e32 v157, v66
	v_mov_b32_e32 v158, v66
	v_mov_b32_e32 v159, v66
	v_mov_b32_e32 v160, v66
	v_mov_b32_e32 v161, v66
	v_mov_b32_e32 v0, v66
	v_mov_b32_e32 v1, v66
	v_mov_b32_e32 v2, v66
	v_mov_b32_e32 v3, v66
	v_mov_b32_e32 v4, v66
	v_mov_b32_e32 v5, v66
	v_mov_b32_e32 v6, v66
	v_mov_b32_e32 v7, v66
	v_mov_b32_e32 v8, v66
	v_mov_b32_e32 v9, v66
	v_mov_b32_e32 v10, v66
	v_mov_b32_e32 v11, v66
	v_mov_b32_e32 v14, v66
	v_mov_b32_e32 v15, v66
	v_mov_b32_e32 v16, v66
	v_mov_b32_e32 v17, v66
	v_mov_b32_e32 v18, v66
	v_mov_b32_e32 v19, v66
	v_mov_b32_e32 v20, v66
	v_mov_b32_e32 v21, v66
	v_mov_b32_e32 v22, v66
	v_mov_b32_e32 v23, v66
	v_mov_b32_e32 v24, v66
	v_mov_b32_e32 v25, v66
	v_mov_b32_e32 v26, v66
	v_mov_b32_e32 v27, v66
	v_mov_b32_e32 v28, v66
	v_mov_b32_e32 v29, v66
	v_mov_b32_e32 v30, v66
	v_mov_b32_e32 v31, v66
	v_mov_b32_e32 v32, v66
	v_mov_b32_e32 v33, v66
	v_mov_b32_e32 v34, v66
	v_mov_b32_e32 v35, v66
	v_mov_b32_e32 v36, v66
	v_mov_b32_e32 v37, v66
	v_mov_b32_e32 v38, v66
	v_mov_b32_e32 v39, v66
	v_mov_b32_e32 v40, v66
	v_mov_b32_e32 v41, v66
	v_mov_b32_e32 v42, v66
	v_mov_b32_e32 v43, v66
	v_mov_b32_e32 v44, v66
	v_mov_b32_e32 v45, v66
	v_mov_b32_e32 v46, v66
	v_mov_b32_e32 v47, v66
	v_mov_b32_e32 v48, v66
	v_mov_b32_e32 v49, v66
	v_mov_b32_e32 v50, v66
	v_mov_b32_e32 v51, v66
	v_mov_b32_e32 v52, v66
	v_mov_b32_e32 v53, v66
	v_mov_b32_e32 v54, v66
	v_mov_b32_e32 v55, v66
	v_mov_b32_e32 v56, v66
	v_mov_b32_e32 v57, v66
	v_mov_b32_e32 v58, v66
	v_mov_b32_e32 v59, v66
	v_mov_b32_e32 v60, v66
	v_mov_b32_e32 v61, v66
	v_mov_b32_e32 v62, v66
	v_mov_b32_e32 v63, v66
	v_mov_b32_e32 v64, v66
	v_mov_b32_e32 v65, v66
	s_branch .LBB0_1039

; __device__ __forceinline__ int opaque_bid() { int t = blockIdx.x * 2 + half_id(); asm volatile("" : "+s"(t)); return t; }
; __global__ void __launch_bounds__(512, 2) fwd_megakernel(Params p) {
;     ...
;         const WS ws = make_ws(p);
; #pragma unroll 1
;         for (int u = opaque_bid(); u < 8 * 4 * 33 + 64; u += NVB) {
;           if (u < 448) gla_decay_unit(p, ws, j, u); else if (u < 512) conv_unit(p, ws, j, u - 448); else gla_decay_unit(p, ws, j, u - 64);
.Lp5_d:
	s_mov_b64 s[10:11], s[6:7]
	s_mov_b64 s[8:9], s[4:5]
	v_mov_b32_e32 v0, s10
	v_mov_b32_e32 v1, s11
	v_readfirstlane_b32 s5, v175
	s_lshr_b32 s5, s5, 8
	v_readfirstlane_b32 s4, v0
	v_mov_b32_e32 v0, s8
	v_mov_b32_e32 v2, s9
	s_add_i32 s48, s5, s69
	s_cmpk_gt_i32 s48, 0x45f
	v_readfirstlane_b32 s5, v1
	s_cbranch_scc1 .LBB0_1266
	s_add_u32 s50, s4, 0x4284000
	s_addc_u32 s51, s5, 0
	s_add_u32 s52, s4, 0x8304000
	s_addc_u32 s53, s5, 0
	s_add_u32 s54, s4, 0x9324000
	s_addc_u32 s55, s5, 0
	s_add_u32 s56, s4, 0xe3c4000
	s_addc_u32 s57, s5, 0
	s_add_u32 s6, s4, 0xe649000
	v_readlane_b32 s3, v240, 29
	s_addc_u32 s7, s5, 0
	s_lshl_b32 s36, s3, 14
	s_lshl_b32 s4, s48, 7
	s_lshl_b32 s58, s3, 15
	s_mov_b32 s59, s93
	s_lshl_b32 s12, s3, 9
	s_lshl_b32 s13, s3, 10
	s_mov_b32 s37, s93
	s_or_b32 s96, s36, 0x1000
	s_mov_b32 s97, s93
	s_or_b32 s74, s36, 0x2000
	s_mov_b32 s75, s93
	s_or_b32 s72, s36, 0x3000
	s_mov_b32 s73, s93
	s_add_i32 s70, s48, 0xfffffe40
	s_add_i32 s71, s4, 0xffff2000
	s_branch .LBB0_1199

; __device__ __forceinline__ int opaque_bid() { int t = blockIdx.x * 2 + half_id(); asm volatile("" : "+s"(t)); return t; }
; __global__ void __launch_bounds__(512, 2) fwd_megakernel(Params p) {
;     ...
;       xcd_barrier(xb);
;       {
; #pragma unroll 1
;         for (int rep = 0; rep < REP_E2; ++rep)
; #pragma unroll 1
;         for (int u = opaque_bid(); u < 512; u += NVB) {
;           if (u & 1) { const WS ws = make_ws(p); rglru_unit(p, ws, j, u >> 1, rep < REP_E2 - 1); }
;           else { const WS ws = make_ws(p); gla_unit(p, ws, u >> 1, rep < REP_E2 - 1); }
;         }
.LBB0_1314:
	s_or_b64 exec, exec, s[4:5]
	v_readfirstlane_b32 s4, v175
	v_readlane_b32 s74, v241, 3
	s_lshr_b32 s4, s4, 8
	s_add_i32 s85, s4, s74
	s_waitcnt lgkmcnt(0)
	s_barrier
	s_cmp_lg_u32 s100, 0
	s_cbranch_scc1 .Lp6_h1
	s_setprio 1
	s_branch .Lp6_d
.Lp6_h1:
	s_setprio 0
.Lp6_d:
	s_cmpk_gt_i32 s85, 0x1ff
	s_cbranch_scc1 .LBB0_1669
	v_readlane_b32 s3, v240, 29
	s_lshl_b32 s30, s3, 19
	s_lshl_b32 s31, s3, 10
	s_bitcmp1_b32 s85, 0
	s_cselect_b64 s[94:95], -1, 0
	s_branch .LBB0_1318

; __device__ __forceinline__ int opaque_tid() { int t = threadIdx.x & 255; asm volatile("" : "+v"(t)); return t; }
; __device__ __forceinline__ int opaque_bid() { int t = blockIdx.x * 2 + half_id(); asm volatile("" : "+s"(t)); return t; }
; __device__ __forceinline__ void phase_gla_norm(const Params& p, const WS& ws, int j) {
;   const size_t gtid = (size_t)opaque_bid() * 256 + opaque_tid(), gsz = (size_t)NVB * 256;
;   const float* gn = p.ab_gla_norm + j * 256;
; #pragma unroll 4
;   for (size_t idx = gtid; idx < (size_t)M_ * 128; idx += gsz) {
;     const size_t row = idx >> 7; const int c8 = (int)(idx & 127); const int hd = c8 >> 5; const int dv = (c8 & 31) * 8;
;     const float4 s0 = *(const float4*)(ws.SSQ + row * 32 + hd * 8), s1 = *(const float4*)(ws.SSQ + row * 32 + hd * 8 + 4);
; __global__ void __launch_bounds__(512, 2) fwd_megakernel(Params p) {
;     ...
;       xcd_barrier(xb);
;       {
;         const WS ws = make_ws(p);
;         phase_gla_norm(p, ws, j);
.Lp7_d:
	v_mov_b32_e32 v0, s6
	v_mov_b32_e32 v1, s7
	s_nop 0
	v_readfirstlane_b32 s8, v0
	v_mov_b32_e32 v0, s4
	v_readfirstlane_b32 s4, v175
	v_readfirstlane_b32 s9, v1
	v_mov_b32_e32 v1, s5
	s_lshr_b32 s4, s4, 8
	s_add_i32 s12, s4, s69
	s_ashr_i32 s13, s12, 31
	v_mov_b32_e32 v0, v186
	s_lshl_b64 s[4:5], s[12:13], 8
	s_nop 0
	v_ashrrev_i32_e32 v1, 31, v0
	v_lshl_add_u64 v[2:3], s[4:5], 0, v[0:1]
	s_mov_b64 s[4:5], 0x204000
	v_cmp_gt_u64_e32 vcc, s[4:5], v[2:3]
	s_and_saveexec_b64 s[4:5], vcc
	s_cbranch_execz .LBB0_1726
	s_add_u32 s6, s8, 0xa344000
	s_addc_u32 s7, s9, 0
	s_add_u32 s38, s8, 0xc384000
	s_load_dwordx2 s[10:11], s[0:1], 0x70
	s_addc_u32 s39, s9, 0
	s_add_u32 s40, s8, 0xe445000
	v_readlane_b32 s3, v240, 29
	s_addc_u32 s41, s9, 0
	s_lshl_b32 s92, s3, 8
	s_lshl_b64 s[8:9], s[92:93], 2
	s_waitcnt lgkmcnt(0)
	s_add_u32 s42, s10, s8
	s_addc_u32 s43, s11, s9
	s_lshl_b64 s[8:9], s[12:13], 11
	v_lshl_add_u64 v[0:1], v[0:1], 3, s[8:9]
	s_mov_b64 s[44:45], 0
	s_branch .LBB0_1722

; __device__ __forceinline__ void rem_tile(int pos, int& mt, int& nt) { if (pos < 65) { mt = pos; nt = 40; } else { mt = 64; nt = pos - 65; } }
;     ...
;     auto issue = [&](u32x4 (&ra)[4], u32x4 (&rb)[2], u32x4& rx) {
;       const int idc = l_id < last_id ? l_id : last_id;
;       int mt, nt; if (TMAP == 1) rem_tile(idc, mt, nt); else tile_of(idc, ntn, mt, nt);
;       const bf16_t* A = (l_kt < ktsplit) ? A0 : A1;
;       const int kk = (l_kt < ktsplit) ? l_kt : l_kt - ktsplit;
;       const int arow = mt * 2 * BMH + hh * BMH + srow;
;       const bf16_t* akb = A + kk * kstride + (tid & 7) * 8;
;       const bf16_t* wp = W + (size_t)(nt * 128 + wrow) * K + l_kt * 64 + (tid5 & 7) * 8;
; #pragma unroll
;       for (int i = 0; i < 4; ++i) {
;         int r = arow + 32 * i; r = r < M_ ? r : M_ - 1;
;         ra[i] = *(const u32x4*)(akb + (size_t)r * lda);
;       }
; #pragma unroll
;       for (int i = 0; i < 2; ++i) rb[i] = *(const u32x4*)(wp + (size_t)i * 64 * K);
;       if (TI == 5) rx = *(const u32x4*)(akb + (size_t)(arow - srow + 128) * lda);
;       if (++l_kt == nk) { l_kt = 0; l_id += G; }
;     };
;     auto store = [&](const u32x4 (&ra)[4], const u32x4 (&rb)[2], const u32x4& rx, int buf) {
; #pragma unroll
;       for (int i = 0; i < 4; ++i) {
;         if (RS) ss[i] += sumsq8(__builtin_bit_cast(bf16x8, ra[i]));
;         *(u32x4*)(As + buf * ASTG + i * 4096 + soff) = ra[i];
;       }
; #pragma unroll
;       for (int i = 0; i < 2; ++i) *(u32x4*)(Bs + buf * 16384 + i * 8192 + woff) = rb[i];
;       if (TI == 5) {
;         if (RS) ss[4] += sumsq8(__builtin_bit_cast(bf16x8, rx));
;         if (srow == 0) *(u32x4*)(Ax0 + buf * 128 + ((tid & 7) << 4)) = rx;
;     ...
;     issue(ra0, rb0, rx0);
;     issue(ra1, rb1, rx1);
;     store(ra0, rb0, rx0, 0);
.Lp8_d:
	s_waitcnt vmcnt(0)
	v_mov_b32_e32 v13, 0x10200
	v_mov_b32_e32 v0, s6
	v_mov_b32_e32 v1, s7
	s_mov_b32 s6, s68
	v_readfirstlane_b32 s44, v0
	v_readfirstlane_b32 s45, v1
	v_mov_b32_e32 v0, s4
	v_mov_b32_e32 v1, s5
	s_and_b32 s7, s6, 7
	s_mul_i32 s7, s7, s75
	s_ashr_i32 s6, s6, 3
	s_add_i32 s12, s7, s6
	v_readfirstlane_b32 s4, v0
	v_readfirstlane_b32 s5, v1
	v_readfirstlane_b32 s6, v175
	v_mov_b32_e32 v10, v186
	v_mov_b32_e32 v11, v175
	s_cmpk_lt_i32 s12, 0x200
	s_cbranch_scc0 .LBB0_1824
	s_add_u32 s46, s44, 0x62c4000
	s_addc_u32 s47, s45, 0
	v_readlane_b32 s8, v240, 30
	v_readlane_b32 s9, v240, 31
	s_add_u32 s4, s4, s8
	s_addc_u32 s5, s5, s9
	s_add_u32 s48, s4, 0xa40000
	s_addc_u32 s49, s5, 0
	s_sub_i32 s4, 0x1ff, s12
	v_readlane_b32 s5, v240, 5
	s_mul_hi_u32 s5, s4, s5
	s_lshr_b32 s9, s6, 8
	s_mul_i32 s6, s5, s77
	s_sub_i32 s4, s4, s6
	s_add_i32 s6, s5, 1
	s_sub_i32 s7, s4, s77
	s_cmp_ge_u32 s4, s77
	s_cselect_b32 s5, s6, s5
	s_cselect_b32 s4, s7, s4
	s_add_i32 s6, s5, 1
	s_cmp_ge_u32 s4, s77
	s_cselect_b32 s4, s6, s5
	s_xor_b32 s4, s4, s85
	s_sub_i32 s8, s4, s85
	s_load_dwordx2 s[4:5], s[0:1], 0x110
	v_ashrrev_i32_e32 v173, 3, v10
	s_mul_i32 s30, s9, 0x81
	v_add_u32_e32 v176, s30, v173
	v_lshlrev_b32_e32 v0, 3, v10
	s_waitcnt lgkmcnt(0)
	s_mul_i32 s13, s8, s4
	s_add_i32 s13, s13, s12
	s_min_i32 s4, s12, s13
	s_ashr_i32 s5, s4, 31
	s_lshr_b32 s5, s5, 26
	s_add_i32 s5, s4, s5
	s_ashr_i32 s5, s5, 6
	s_lshl_b32 s6, s5, 3
	s_and_b32 s7, s4, 7
	s_or_b32 s6, s6, s7
	s_mulk_i32 s6, 0x102
	v_add_u32_e32 v16, s6, v176
	s_lshl_b32 s5, s5, 10
	s_lshl_b32 s4, s4, 4
	v_lshlrev_b32_e32 v2, 3, v11
	v_and_b32_e32 v0, 56, v0
	s_sub_i32 s4, s4, s5
	v_and_b32_e32 v20, 56, v2
	v_min_i32_e32 v2, 0x407f, v16
	v_min_i32_e32 v6, 0x405f, v16
	v_ashrrev_i32_e32 v174, 3, v11
	v_lshlrev_b32_e32 v168, 1, v0
	v_mov_b32_e32 v169, v12
	s_and_b32 s4, s4, 0xffffff80
	v_ashrrev_i32_e32 v3, 31, v2
	v_ashrrev_i32_e32 v7, 31, v6
	v_lshl_add_u64 v[8:9], s[46:47], 0, v[168:169]
	v_add_u32_e32 v0, s4, v174
	v_lshlrev_b64 v[2:3], 11, v[2:3]
	v_lshlrev_b64 v[6:7], 11, v[6:7]
	s_mov_b64 s[4:5], 0x10000
	v_lshl_add_u64 v[4:5], v[8:9], 0, v[2:3]
	v_lshl_add_u64 v[6:7], v[6:7], 0, s[4:5]
	v_lshl_add_u64 v[14:15], v[8:9], 0, v[6:7]
	global_load_dwordx4 v[38:41], v[4:5], off
	global_load_dwordx4 v[42:45], v[14:15], off
	v_min_i32_e32 v4, 0x403f, v16
	v_ashrrev_i32_e32 v5, 31, v4
	v_min_i32_e32 v16, 0x401f, v16
	v_ashrrev_i32_e32 v1, 31, v0
	v_lshlrev_b64 v[4:5], 11, v[4:5]
	s_mov_b64 s[4:5], 0x20000
	v_ashrrev_i32_e32 v17, 31, v16
	v_lshl_add_u64 v[14:15], v[4:5], 0, s[4:5]
	v_lshlrev_b64 v[16:17], 11, v[16:17]
	s_mov_b64 s[4:5], 0x30000
	v_lshlrev_b64 v[0:1], 12, v[0:1]
	v_lshl_add_u64 v[16:17], v[16:17], 0, s[4:5]
	v_lshl_add_u64 v[0:1], s[48:49], 0, v[0:1]
	v_lshlrev_b32_e32 v170, 1, v20
	v_mov_b32_e32 v171, v12
	s_add_i32 s4, s6, s30
	v_lshl_add_u64 v[24:25], v[0:1], 0, v[170:171]
	s_mov_b32 s3, 0x40000
	s_addk_i32 s4, 0x80
	v_lshl_add_u64 v[0:1], s[44:45], 0, v[168:169]
	s_mov_b64 s[6:7], 0x62c4080
	v_lshl_add_u64 v[4:5], v[8:9], 0, v[14:15]
	v_add_co_u32_e32 v28, vcc, s3, v24
	s_ashr_i32 s5, s4, 31
	v_lshl_add_u64 v[32:33], v[0:1], 0, s[6:7]
	v_lshl_add_u64 v[18:19], v[8:9], 0, v[16:17]
	global_load_dwordx4 v[46:49], v[4:5], off
	global_load_dwordx4 v[50:53], v[18:19], off
	v_addc_co_u32_e32 v29, vcc, 0, v25, vcc
	v_lshl_add_u64 v[0:1], v[32:33], 0, v[2:3]
	v_lshl_add_u64 v[4:5], v[32:33], 0, v[6:7]
	v_lshl_add_u64 v[14:15], v[32:33], 0, v[14:15]
	v_lshl_add_u64 v[20:21], v[32:33], 0, v[16:17]
	s_lshl_b64 s[6:7], s[4:5], 11
	global_load_dwordx4 v[0:3], v[0:1], off
	s_nop 0
	global_load_dwordx4 v[4:7], v[4:5], off
	s_nop 0
	global_load_dwordx4 v[16:19], v[14:15], off
	s_nop 0
	global_load_dwordx4 v[20:23], v[20:21], off
	s_nop 0
	global_load_dwordx4 v[54:57], v[24:25], off
	s_nop 0
	global_load_dwordx4 v[24:27], v[24:25], off offset:128
	s_nop 0
	global_load_dwordx4 v[58:61], v[28:29], off
	s_nop 0
	global_load_dwordx4 v[28:31], v[28:29], off offset:128
	v_lshl_add_u64 v[14:15], v[32:33], 0, s[6:7]
	global_load_dwordx4 v[32:35], v[14:15], off
	s_mul_i32 s9, s9, 0x12800
	v_xor_b32_e32 v14, v173, v10
	v_add_u32_e32 v36, s9, v13
	v_lshlrev_b32_e32 v13, 7, v173
	v_lshlrev_b32_e32 v14, 4, v14
	s_movk_i32 s3, 0x70
	v_xor_b32_e32 v11, v174, v11
	v_and_or_b32 v13, v14, s3, v13
	v_lshlrev_b32_e32 v14, 7, v174
	v_lshlrev_b32_e32 v11, 4, v11
	v_and_or_b32 v177, v11, s3, v14
	v_add_u32_e32 v178, s9, v13
	v_cmp_gt_u32_e64 s[38:39], 8, v10
	s_waitcnt vmcnt(12)
	ds_write_b128 v178, v[38:41]
	s_waitcnt vmcnt(11)
	ds_write_b128 v178, v[42:45] offset:4096
	s_waitcnt vmcnt(10)
	ds_write_b128 v178, v[46:49] offset:8192
	s_waitcnt vmcnt(9)
	ds_write_b128 v178, v[50:53] offset:12288
	s_waitcnt vmcnt(4)
	ds_write_b128 v177, v[54:57] offset:32768
	s_waitcnt vmcnt(2)
	ds_write_b128 v177, v[58:61] offset:40960
	s_and_saveexec_b64 s[6:7], s[38:39]
	s_cbranch_execz .LBB0_1777
	s_lshl_b64 s[4:5], s[4:5], 10
	v_lshl_add_u64 v[8:9], s[4:5], 1, v[8:9]
	global_load_dwordx4 v[38:41], v[8:9], off
	v_lshl_add_u32 v8, v10, 4, v36
	s_waitcnt vmcnt(0)
	ds_write_b128 v8, v[38:41]
